# E1/E2/E3 row sum-of-squares all-reduce: six 6-step ds_bpermute butterflies replaced by DPP + permlane16/32 swap, on top of v062
# speedup vs baseline: 1.0051x; 1.0051x over previous
; __device__ __forceinline__ unsigned pk2(float lo, float hi) { const f32x2_pk v = {lo, hi}; return __builtin_bit_cast(unsigned, __builtin_convertvector(v, bf16x2_pk)); }
; __device__ __forceinline__ float bflo(unsigned w) { return __uint_as_float(w << 16); }
; __device__ __forceinline__ float bfhi(unsigned w) { return __uint_as_float(w & 0xffff0000u); }
; #define RS ((float*)(WSP() + WS_RS))
; template <bool HAS_G, bool HAS_PRE, bool HAS_F, bool HAS_P, bool HIN32, bool HOUT32> ...
;     ...
;         for (int j = 0; j < 4; ++j) { if (HIN32) v[j] = h32[u][j]; else v[j] = (f32x4){bflo(hbr[u][j].x), bfhi(hbr[u][j].x), bflo(hbr[u][j].y), bfhi(hbr[u][j].y)};
;             if (HAS_G) g[j] = (f32x4){bflo(gbr[u][j].x), bfhi(gbr[u][j].x), bflo(gbr[u][j].y), bfhi(gbr[u][j].y)}; }
;         if (m + 2 * NGW < M) E_LOAD(u, m + 2 * NGW);
;         if (HAS_G) {
;             float ss = 0.f;
; #pragma unroll
;             for (int j = 0; j < 4; ++j) ss += (g[j][0] * g[j][0] + g[j][1] * g[j][1]) + (g[j][2] * g[j][2] + g[j][3] * g[j][3]);
;             const float r = __builtin_amdgcn_rsqf(wave_sum(ss) * (1.f / DM) + EPS)    ;
; #pragma unroll
;             for (int j = 0; j < 4; ++j) { v[j] = v[j] + g[j] * r * gp[j];
;                 if (HOUT32) __builtin_nontemporal_store(v[j], (f32x4*)((float*)hout_ + mm * DM + 4 * lane + 256 * j));
;                 else { v2u w; w.x = pk2(v[j][0], v[j][1]); w.y = pk2(v[j][2], v[j][3]); *(v2u*)((bf16*)hout_ + mm * DM + 4 * lane + 256 * j) = w; } }
;         }
;         if (!HAS_G && hout_) {
; #pragma unroll
;             for (int j = 0; j < 4; ++j) { v2u w; w.x = pk2(v[j][0], v[j][1]); w.y = pk2(v[j][2], v[j][3]); *(v2u*)((bf16*)hout_ + mm * DM + 4 * lane + 256 * j) = w; } }
;         if (HAS_PRE) {
;             float ss = 0.f;
; #pragma unroll
;             for (int j = 0; j < 4; ++j) ss += (v[j][0] * v[j][0] + v[j][1] * v[j][1]) + (v[j][2] * v[j][2] + v[j][3] * v[j][3]);
;             const float r = __builtin_amdgcn_rsqf(wave_sum(ss) * (1.f / DM) + EPS)    ;
;             if (lane == 0) RS[mm] = r;
.LBB0_604:
	v_lshlrev_b32_e32 v79, 16, v71
	v_lshlrev_b32_e32 v78, 16, v70
	v_and_b32_e32 v71, 0xffff0000, v71
	v_and_b32_e32 v70, 0xffff0000, v70
	v_pk_mul_f32 v[86:87], v[70:71], v[70:71]
	v_lshlrev_b32_e32 v81, 16, v67
	v_lshlrev_b32_e32 v80, 16, v66
	v_and_b32_e32 v67, 0xffff0000, v67
	v_and_b32_e32 v66, 0xffff0000, v66
	v_pk_fma_f32 v[86:87], v[78:79], v[78:79], v[86:87]
	v_lshlrev_b32_e32 v82, 16, v64
	v_and_b32_e32 v83, 0xffff0000, v64
	v_lshlrev_b32_e32 v64, 16, v65
	v_lshlrev_b32_e32 v84, 16, v60
	v_pk_add_f32 v[86:87], v[86:87], v[86:87] op_sel_hi:[0,1]
	v_pk_mul_f32 v[88:89], v[66:67], v[66:67]
	v_and_b32_e32 v65, 0xffff0000, v65
	v_pk_fma_f32 v[88:89], v[80:81], v[80:81], v[88:89]
	v_mul_f32_e32 v85, v82, v82
	v_mul_f32_e32 v91, v83, v83
	v_mul_f32_e32 v86, v64, v64
	v_mov_b32_e32 v90, v84
	v_and_b32_e32 v98, 0xffff0000, v60
	v_lshlrev_b32_e32 v60, 16, v61
	v_and_b32_e32 v61, 0xffff0000, v61
	v_pk_add_f32 v[88:89], v[88:89], v[88:89] op_sel_hi:[0,1]
	v_pk_fma_f32 v[92:93], v[64:65], v[64:65], v[86:87] op_sel_hi:[1,1,0]
	v_pk_add_f32 v[90:91], v[84:85], v[90:91]
	v_mul_f32_e32 v92, v98, v98
	v_mul_f32_e32 v88, v60, v60
	v_mul_f32_e32 v86, v61, v61
	v_mul_f32_e32 v94, v84, v84
	v_mov_b32_e32 v95, v91
	v_pk_add_f32 v[90:91], v[94:95], v[92:93]
	v_pk_add_f32 v[86:87], v[88:89], v[86:87]
	v_mov_b32_e32 v96, v78
	v_pk_add_f32 v[86:87], v[90:91], v[86:87]
	v_mov_b32_e32 v97, v70
	v_add_f32_e32 v85, v86, v87
	v_mov_b32_e32 v70, v79
	v_and_b32_e32 v87, 0xffff0000, v68
	v_and_b32_e32 v93, 0xffff0000, v56
	v_mov_b32_e32 v78, v80
	v_mov_b32_e32 v79, v66
	v_mov_b32_e32 v66, v81
	v_and_b32_e32 v89, 0xffff0000, v62
	v_and_b32_e32 v91, 0xffff0000, v58
	v_lshlrev_b32_e32 v86, 16, v68
	v_lshlrev_b32_e32 v68, 16, v69
	v_and_b32_e32 v69, 0xffff0000, v69
	s_mov_b32 s7, 0x6800000
	v_lshlrev_b32_e32 v88, 16, v62
	v_lshlrev_b32_e32 v62, 16, v63
	v_and_b32_e32 v63, 0xffff0000, v63
	v_lshlrev_b32_e32 v90, 16, v58
	v_lshlrev_b32_e32 v58, 16, v59
	v_and_b32_e32 v59, 0xffff0000, v59
	v_lshlrev_b32_e32 v92, 16, v56
	v_lshlrev_b32_e32 v56, 16, v57
	v_and_b32_e32 v57, 0xffff0000, v57
	s_waitcnt lgkmcnt(0)
	s_nop 1
	v_add_f32_dpp v85, v85, v85 quad_perm:[1,0,3,2] row_mask:0xf bank_mask:0xf
	s_nop 1
	v_add_f32_dpp v85, v85, v85 quad_perm:[2,3,0,1] row_mask:0xf bank_mask:0xf
	s_nop 1
	v_add_f32_dpp v85, v85, v85 row_half_mirror row_mask:0xf bank_mask:0xf
	s_nop 1
	v_add_f32_dpp v85, v85, v85 row_mirror row_mask:0xf bank_mask:0xf
	v_mov_b32_e32 v94, v85
	s_nop 1
	v_permlane16_swap_b32_e32 v85, v94
	v_add_f32_e32 v85, v85, v94
	v_mov_b32_e32 v94, v85
	s_nop 1
	v_permlane32_swap_b32_e32 v85, v94
	v_add_f32_e32 v85, v85, v94
	v_fmamk_f32 v85, v85, 0x3a800000, v214
	v_rsq_f32_e32 v94, v85
	v_mov_b32_e32 v85, v98
	v_pk_mul_f32 v[96:97], v[94:95], v[96:97] op_sel_hi:[0,1]
	v_pk_mul_f32 v[70:71], v[94:95], v[70:71] op_sel_hi:[0,1]
	v_pk_fma_f32 v[68:69], v[4:5], v[70:71], v[68:69]
	v_pk_fma_f32 v[70:71], v[2:3], v[96:97], v[86:87]
	v_pk_mul_f32 v[60:61], v[60:61], v[94:95] op_sel_hi:[1,0]
	v_pk_mul_f32 v[78:79], v[94:95], v[78:79] op_sel_hi:[0,1]
	v_pk_mul_f32 v[66:67], v[94:95], v[66:67] op_sel_hi:[0,1]
	v_pk_fma_f32 v[60:61], v[16:17], v[60:61], v[56:57]
	v_mul_f32_e32 v56, v71, v71
	v_mul_f32_e32 v57, v69, v69
	v_pk_fma_f32 v[62:63], v[8:9], v[66:67], v[62:63]
	v_pk_fma_f32 v[66:67], v[6:7], v[78:79], v[88:89]
	v_fmac_f32_e32 v56, v70, v70
	v_fmac_f32_e32 v57, v68, v68
	v_add_f32_e32 v56, v56, v57
	v_mul_f32_e32 v57, v67, v67
	v_mul_f32_e32 v80, v63, v63
	v_pk_mul_f32 v[78:79], v[82:83], v[94:95] op_sel_hi:[1,0]
	v_pk_mul_f32 v[64:65], v[64:65], v[94:95] op_sel_hi:[1,0]
	v_fmac_f32_e32 v57, v66, v66
	v_fmac_f32_e32 v80, v62, v62
	v_pk_fma_f32 v[58:59], v[12:13], v[64:65], v[58:59]
	v_pk_fma_f32 v[64:65], v[10:11], v[78:79], v[90:91]
	v_add_f32_e32 v57, v57, v80
	v_add_f32_e32 v56, v56, v57
	v_mul_f32_e32 v57, v65, v65
	v_mul_f32_e32 v80, v59, v59
	v_pk_mul_f32 v[78:79], v[84:85], v[94:95] op_sel_hi:[1,0]
	v_fmac_f32_e32 v57, v64, v64
	v_fmac_f32_e32 v80, v58, v58
	v_pk_fma_f32 v[78:79], v[14:15], v[78:79], v[92:93]
	v_add_f32_e32 v57, v57, v80
	v_add_f32_e32 v56, v57, v56
	v_mul_f32_e32 v57, v79, v79
	v_mul_f32_e32 v80, v61, v61
	v_fmac_f32_e32 v57, v78, v78
	v_fmac_f32_e32 v80, v60, v60
	v_add_f32_e32 v57, v57, v80
	v_add_f32_e32 v56, v57, v56
	ds_bpermute_b32 v57, v72, v56
	v_cvt_pk_bf16_f32 v70, v70, v71
	v_cvt_pk_bf16_f32 v71, v68, v69
	s_waitcnt lgkmcnt(0)
	v_add_f32_e32 v56, v56, v57
	ds_bpermute_b32 v57, v73, v56
	s_waitcnt lgkmcnt(0)
	v_add_f32_e32 v80, v56, v57
	ds_bpermute_b32 v81, v74, v80
	v_lshl_add_u64 v[56:57], s[18:19], 0, v[0:1]
	v_add_co_u32_e32 v68, vcc, s7, v56
	v_cvt_pk_bf16_f32 v56, v66, v67
	s_waitcnt lgkmcnt(0)
	v_add_f32_e32 v80, v80, v81
	ds_bpermute_b32 v81, v75, v80
	v_addc_co_u32_e32 v69, vcc, 0, v57, vcc
	v_cvt_pk_bf16_f32 v57, v62, v63
	global_store_dwordx2 v[68:69], v[56:57], off offset:512
	s_waitcnt lgkmcnt(0)
	v_add_f32_e32 v66, v80, v81
	ds_bpermute_b32 v67, v76, v66
	v_cvt_pk_bf16_f32 v62, v64, v65
	v_cvt_pk_bf16_f32 v63, v58, v59
	v_cvt_pk_bf16_f32 v58, v78, v79
	v_cvt_pk_bf16_f32 v59, v60, v61
	s_waitcnt lgkmcnt(0)
	v_add_f32_e32 v56, v66, v67
	ds_bpermute_b32 v57, v77, v56
	global_store_dwordx2 v[68:69], v[70:71], off
	global_store_dwordx2 v[68:69], v[62:63], off offset:1024
	global_store_dwordx2 v[68:69], v[58:59], off offset:1536
	s_and_saveexec_b64 s[20:21], s[4:5]
	s_cbranch_execz .LBB0_606
	s_waitcnt lgkmcnt(0)
	v_add_f32_e32 v56, v56, v57
	v_fmamk_f32 v56, v56, 0x3a800000, v214
	v_rsq_f32_e32 v56, v56
	global_store_dword v1, v56, s[14:15]

; __device__ __forceinline__ unsigned pk2(float lo, float hi) { const f32x2_pk v = {lo, hi}; return __builtin_bit_cast(unsigned, __builtin_convertvector(v, bf16x2_pk)); }
; __device__ __forceinline__ float bflo(unsigned w) { return __uint_as_float(w << 16); }
; __device__ __forceinline__ float bfhi(unsigned w) { return __uint_as_float(w & 0xffff0000u); }
; #define RS ((float*)(WSP() + WS_RS))
; template <bool HAS_G, bool HAS_PRE, bool HAS_F, bool HAS_P, bool HIN32, bool HOUT32> ...
;     ...
;         for (int j = 0; j < 4; ++j) { if (HIN32) v[j] = h32[u][j]; else v[j] = (f32x4){bflo(hbr[u][j].x), bfhi(hbr[u][j].x), bflo(hbr[u][j].y), bfhi(hbr[u][j].y)};
;             if (HAS_G) g[j] = (f32x4){bflo(gbr[u][j].x), bfhi(gbr[u][j].x), bflo(gbr[u][j].y), bfhi(gbr[u][j].y)}; }
;         if (m + 2 * NGW < M) E_LOAD(u, m + 2 * NGW);
;         if (HAS_G) {
;             float ss = 0.f;
; #pragma unroll
;             for (int j = 0; j < 4; ++j) ss += (g[j][0] * g[j][0] + g[j][1] * g[j][1]) + (g[j][2] * g[j][2] + g[j][3] * g[j][3]);
;             const float r = __builtin_amdgcn_rsqf(wave_sum(ss) * (1.f / DM) + EPS)    ;
; #pragma unroll
;             for (int j = 0; j < 4; ++j) { v[j] = v[j] + g[j] * r * gp[j];
;                 if (HOUT32) __builtin_nontemporal_store(v[j], (f32x4*)((float*)hout_ + mm * DM + 4 * lane + 256 * j));
;                 else { v2u w; w.x = pk2(v[j][0], v[j][1]); w.y = pk2(v[j][2], v[j][3]); *(v2u*)((bf16*)hout_ + mm * DM + 4 * lane + 256 * j) = w; } }
;         }
;         if (!HAS_G && hout_) {
; #pragma unroll
;             for (int j = 0; j < 4; ++j) { v2u w; w.x = pk2(v[j][0], v[j][1]); w.y = pk2(v[j][2], v[j][3]); *(v2u*)((bf16*)hout_ + mm * DM + 4 * lane + 256 * j) = w; } }
;         if (HAS_PRE) {
;             float ss = 0.f;
; #pragma unroll
;             for (int j = 0; j < 4; ++j) ss += (v[j][0] * v[j][0] + v[j][1] * v[j][1]) + (v[j][2] * v[j][2] + v[j][3] * v[j][3]);
;             const float r = __builtin_amdgcn_rsqf(wave_sum(ss) * (1.f / DM) + EPS)    ;
;             if (lane == 0) RS[mm] = r;
.LBB0_608:
	v_lshlrev_b32_e32 v79, 16, v55
	v_lshlrev_b32_e32 v78, 16, v54
	v_and_b32_e32 v55, 0xffff0000, v55
	v_and_b32_e32 v54, 0xffff0000, v54
	v_pk_mul_f32 v[86:87], v[54:55], v[54:55]
	v_lshlrev_b32_e32 v81, 16, v53
	v_lshlrev_b32_e32 v80, 16, v52
	v_and_b32_e32 v53, 0xffff0000, v53
	v_and_b32_e32 v52, 0xffff0000, v52
	v_pk_fma_f32 v[86:87], v[78:79], v[78:79], v[86:87]
	v_lshlrev_b32_e32 v82, 16, v50
	v_and_b32_e32 v83, 0xffff0000, v50
	v_lshlrev_b32_e32 v50, 16, v51
	v_lshlrev_b32_e32 v84, 16, v48
	v_pk_add_f32 v[86:87], v[86:87], v[86:87] op_sel_hi:[0,1]
	v_pk_mul_f32 v[88:89], v[52:53], v[52:53]
	v_and_b32_e32 v51, 0xffff0000, v51
	v_pk_fma_f32 v[88:89], v[80:81], v[80:81], v[88:89]
	v_mul_f32_e32 v85, v82, v82
	v_mul_f32_e32 v91, v83, v83
	v_mul_f32_e32 v86, v50, v50
	v_mov_b32_e32 v90, v84
	v_and_b32_e32 v98, 0xffff0000, v48
	v_lshlrev_b32_e32 v48, 16, v49
	v_and_b32_e32 v49, 0xffff0000, v49
	v_pk_add_f32 v[88:89], v[88:89], v[88:89] op_sel_hi:[0,1]
	v_pk_fma_f32 v[92:93], v[50:51], v[50:51], v[86:87] op_sel_hi:[1,1,0]
	v_pk_add_f32 v[90:91], v[84:85], v[90:91]
	v_mul_f32_e32 v92, v98, v98
	v_mul_f32_e32 v88, v48, v48
	v_mul_f32_e32 v86, v49, v49
	v_mul_f32_e32 v94, v84, v84
	v_mov_b32_e32 v95, v91
	v_pk_add_f32 v[90:91], v[94:95], v[92:93]
	v_pk_add_f32 v[86:87], v[88:89], v[86:87]
	v_mov_b32_e32 v96, v78
	v_pk_add_f32 v[86:87], v[90:91], v[86:87]
	v_mov_b32_e32 v97, v54
	v_add_f32_e32 v85, v86, v87
	v_mov_b32_e32 v54, v79
	v_and_b32_e32 v87, 0xffff0000, v46
	v_and_b32_e32 v93, 0xffff0000, v40
	v_mov_b32_e32 v78, v80
	v_mov_b32_e32 v79, v52
	v_mov_b32_e32 v52, v81
	v_and_b32_e32 v89, 0xffff0000, v44
	v_and_b32_e32 v91, 0xffff0000, v42
	v_lshlrev_b32_e32 v86, 16, v46
	v_lshlrev_b32_e32 v46, 16, v47
	v_and_b32_e32 v47, 0xffff0000, v47
	s_add_i32 s20, s28, s2
	v_lshlrev_b32_e32 v88, 16, v44
	v_lshlrev_b32_e32 v44, 16, v45
	v_and_b32_e32 v45, 0xffff0000, v45
	s_ashr_i32 s21, s20, 31
	v_lshlrev_b32_e32 v90, 16, v42
	v_lshlrev_b32_e32 v42, 16, v43
	v_and_b32_e32 v43, 0xffff0000, v43
	s_lshl_b64 s[22:23], s[20:21], 11
	v_lshlrev_b32_e32 v92, 16, v40
	v_lshlrev_b32_e32 v40, 16, v41
	v_and_b32_e32 v41, 0xffff0000, v41
	s_waitcnt lgkmcnt(0)
	s_nop 1
	v_add_f32_dpp v85, v85, v85 quad_perm:[1,0,3,2] row_mask:0xf bank_mask:0xf
	s_nop 1
	v_add_f32_dpp v85, v85, v85 quad_perm:[2,3,0,1] row_mask:0xf bank_mask:0xf
	s_nop 1
	v_add_f32_dpp v85, v85, v85 row_half_mirror row_mask:0xf bank_mask:0xf
	s_nop 1
	v_add_f32_dpp v85, v85, v85 row_mirror row_mask:0xf bank_mask:0xf
	v_mov_b32_e32 v94, v85
	s_nop 1
	v_permlane16_swap_b32_e32 v85, v94
	v_add_f32_e32 v85, v85, v94
	v_mov_b32_e32 v94, v85
	s_nop 1
	v_permlane32_swap_b32_e32 v85, v94
	v_add_f32_e32 v85, v85, v94
	v_fmamk_f32 v85, v85, 0x3a800000, v214
	v_rsq_f32_e32 v94, v85
	v_mov_b32_e32 v85, v98
	v_pk_mul_f32 v[96:97], v[94:95], v[96:97] op_sel_hi:[0,1]
	v_pk_mul_f32 v[54:55], v[94:95], v[54:55] op_sel_hi:[0,1]
	v_pk_fma_f32 v[46:47], v[4:5], v[54:55], v[46:47]
	v_pk_fma_f32 v[54:55], v[2:3], v[96:97], v[86:87]
	v_pk_mul_f32 v[48:49], v[48:49], v[94:95] op_sel_hi:[1,0]
	v_pk_mul_f32 v[78:79], v[94:95], v[78:79] op_sel_hi:[0,1]
	v_pk_mul_f32 v[52:53], v[94:95], v[52:53] op_sel_hi:[0,1]
	v_pk_fma_f32 v[48:49], v[16:17], v[48:49], v[40:41]
	v_mul_f32_e32 v40, v55, v55
	v_mul_f32_e32 v41, v47, v47
	v_pk_fma_f32 v[44:45], v[8:9], v[52:53], v[44:45]
	v_pk_fma_f32 v[52:53], v[6:7], v[78:79], v[88:89]
	v_fmac_f32_e32 v40, v54, v54
	v_fmac_f32_e32 v41, v46, v46
	v_add_f32_e32 v40, v40, v41
	v_mul_f32_e32 v41, v53, v53
	v_mul_f32_e32 v80, v45, v45
	v_pk_mul_f32 v[78:79], v[82:83], v[94:95] op_sel_hi:[1,0]
	v_pk_mul_f32 v[50:51], v[50:51], v[94:95] op_sel_hi:[1,0]
	v_fmac_f32_e32 v41, v52, v52
	v_fmac_f32_e32 v80, v44, v44
	v_pk_fma_f32 v[42:43], v[12:13], v[50:51], v[42:43]
	v_pk_fma_f32 v[50:51], v[10:11], v[78:79], v[90:91]
	v_add_f32_e32 v41, v41, v80
	v_add_f32_e32 v40, v40, v41
	v_mul_f32_e32 v41, v51, v51
	v_mul_f32_e32 v80, v43, v43
	v_pk_mul_f32 v[78:79], v[84:85], v[94:95] op_sel_hi:[1,0]
	v_fmac_f32_e32 v41, v50, v50
	v_fmac_f32_e32 v80, v42, v42
	v_pk_fma_f32 v[78:79], v[14:15], v[78:79], v[92:93]
	v_add_f32_e32 v41, v41, v80
	v_add_f32_e32 v40, v41, v40
	v_mul_f32_e32 v41, v79, v79
	v_mul_f32_e32 v80, v49, v49
	v_fmac_f32_e32 v41, v78, v78
	v_fmac_f32_e32 v80, v48, v48
	v_add_f32_e32 v41, v41, v80
	v_add_f32_e32 v40, v41, v40
	ds_bpermute_b32 v41, v72, v40
	v_lshl_add_u64 v[80:81], v[18:19], 0, s[22:23]
	s_waitcnt lgkmcnt(0)
	v_add_f32_e32 v40, v40, v41
	ds_bpermute_b32 v41, v73, v40
	s_waitcnt lgkmcnt(0)
	v_add_f32_e32 v40, v40, v41
	ds_bpermute_b32 v41, v74, v40
	s_waitcnt lgkmcnt(0)
	v_add_f32_e32 v82, v40, v41
	ds_bpermute_b32 v83, v75, v82
	v_cvt_pk_bf16_f32 v41, v46, v47
	v_cvt_pk_bf16_f32 v40, v54, v55
	global_store_dwordx2 v[80:81], v[40:41], off
	v_cvt_pk_bf16_f32 v40, v52, v53
	s_waitcnt lgkmcnt(0)
	v_add_f32_e32 v46, v82, v83
	ds_bpermute_b32 v47, v76, v46
	v_cvt_pk_bf16_f32 v41, v44, v45
	global_store_dwordx2 v[80:81], v[40:41], off offset:512
	v_cvt_pk_bf16_f32 v44, v50, v51
	v_cvt_pk_bf16_f32 v45, v42, v43
	s_waitcnt lgkmcnt(0)
	v_add_f32_e32 v40, v46, v47
	ds_bpermute_b32 v41, v77, v40
	v_cvt_pk_bf16_f32 v42, v78, v79
	v_cvt_pk_bf16_f32 v43, v48, v49
	global_store_dwordx2 v[80:81], v[44:45], off offset:1024
	global_store_dwordx2 v[80:81], v[42:43], off offset:1536
	s_and_saveexec_b64 s[22:23], s[4:5]
	s_cbranch_execz .LBB0_601
	s_waitcnt lgkmcnt(0)
	v_add_f32_e32 v40, v40, v41
	v_fmamk_f32 v40, v40, 0x3a800000, v214
	v_rsq_f32_e32 v40, v40
	s_lshl_b64 s[20:21], s[20:21], 2
	s_add_u32 s20, s25, s20
	s_addc_u32 s21, s26, s21
	global_store_dword v1, v40, s[20:21]
	s_branch .LBB0_601

; __device__ __forceinline__ unsigned pk2(float lo, float hi) { const f32x2_pk v = {lo, hi}; return __builtin_bit_cast(unsigned, __builtin_convertvector(v, bf16x2_pk)); }
; __device__ __forceinline__ float bflo(unsigned w) { return __uint_as_float(w << 16); }
; __device__ __forceinline__ float bfhi(unsigned w) { return __uint_as_float(w & 0xffff0000u); }
; #define RS ((float*)(WSP() + WS_RS))
; template <bool HAS_G, bool HAS_PRE, bool HAS_F, bool HAS_P, bool HIN32, bool HOUT32> ...
;     ...
;         for (int j = 0; j < 4; ++j) { if (HIN32) v[j] = h32[u][j]; else v[j] = (f32x4){bflo(hbr[u][j].x), bfhi(hbr[u][j].x), bflo(hbr[u][j].y), bfhi(hbr[u][j].y)};
;             if (HAS_G) g[j] = (f32x4){bflo(gbr[u][j].x), bfhi(gbr[u][j].x), bflo(gbr[u][j].y), bfhi(gbr[u][j].y)}; }
;         if (m + 2 * NGW < M) E_LOAD(u, m + 2 * NGW);
;         if (HAS_G) {
;             float ss = 0.f;
; #pragma unroll
;             for (int j = 0; j < 4; ++j) ss += (g[j][0] * g[j][0] + g[j][1] * g[j][1]) + (g[j][2] * g[j][2] + g[j][3] * g[j][3]);
;             const float r = __builtin_amdgcn_rsqf(wave_sum(ss) * (1.f / DM) + EPS)    ;
; #pragma unroll
;             for (int j = 0; j < 4; ++j) { v[j] = v[j] + g[j] * r * gp[j];
;                 if (HOUT32) __builtin_nontemporal_store(v[j], (f32x4*)((float*)hout_ + mm * DM + 4 * lane + 256 * j));
;                 else { v2u w; w.x = pk2(v[j][0], v[j][1]); w.y = pk2(v[j][2], v[j][3]); *(v2u*)((bf16*)hout_ + mm * DM + 4 * lane + 256 * j) = w; } }
;         }
;         if (!HAS_G && hout_) {
; #pragma unroll
;             for (int j = 0; j < 4; ++j) { v2u w; w.x = pk2(v[j][0], v[j][1]); w.y = pk2(v[j][2], v[j][3]); *(v2u*)((bf16*)hout_ + mm * DM + 4 * lane + 256 * j) = w; } }
;         if (HAS_PRE) {
;             float ss = 0.f;
; #pragma unroll
;             for (int j = 0; j < 4; ++j) ss += (v[j][0] * v[j][0] + v[j][1] * v[j][1]) + (v[j][2] * v[j][2] + v[j][3] * v[j][3]);
;             const float r = __builtin_amdgcn_rsqf(wave_sum(ss) * (1.f / DM) + EPS)    ;
;             if (lane == 0) RS[mm] = r;
.LBB0_987:
	v_lshlrev_b32_e32 v167, 16, v157
	v_lshlrev_b32_e32 v166, 16, v156
	v_and_b32_e32 v157, 0xffff0000, v157
	v_and_b32_e32 v156, 0xffff0000, v156
	v_lshlrev_b32_e32 v169, 16, v153
	v_lshlrev_b32_e32 v168, 16, v152
	v_and_b32_e32 v171, 0xffff0000, v153
	v_and_b32_e32 v170, 0xffff0000, v152
	v_pk_mul_f32 v[152:153], v[156:157], v[156:157]
	v_lshlrev_b32_e32 v172, 16, v150
	v_pk_fma_f32 v[152:153], v[166:167], v[166:167], v[152:153]
	v_and_b32_e32 v173, 0xffff0000, v150
	v_lshlrev_b32_e32 v150, 16, v151
	v_lshlrev_b32_e32 v174, 16, v146
	v_pk_add_f32 v[152:153], v[152:153], v[152:153] op_sel_hi:[0,1]
	v_pk_mul_f32 v[176:177], v[170:171], v[170:171]
	v_and_b32_e32 v151, 0xffff0000, v151
	v_pk_fma_f32 v[176:177], v[168:169], v[168:169], v[176:177]
	v_mul_f32_e32 v175, v172, v172
	v_mul_f32_e32 v179, v173, v173
	v_mul_f32_e32 v152, v150, v150
	v_mov_b32_e32 v178, v174
	v_and_b32_e32 v165, 0xffff0000, v146
	v_lshlrev_b32_e32 v146, 16, v147
	v_and_b32_e32 v147, 0xffff0000, v147
	v_pk_add_f32 v[176:177], v[176:177], v[176:177] op_sel_hi:[0,1]
	v_pk_fma_f32 v[180:181], v[150:151], v[150:151], v[152:153] op_sel_hi:[1,1,0]
	v_pk_add_f32 v[178:179], v[174:175], v[178:179]
	v_mul_f32_e32 v180, v165, v165
	v_mul_f32_e32 v176, v146, v146
	v_mul_f32_e32 v152, v147, v147
	v_mul_f32_e32 v182, v174, v174
	v_mov_b32_e32 v183, v179
	v_pk_add_f32 v[178:179], v[182:183], v[180:181]
	v_pk_add_f32 v[152:153], v[176:177], v[152:153]
	v_mov_b32_e32 v184, v166
	v_pk_add_f32 v[152:153], v[178:179], v[152:153]
	v_mov_b32_e32 v185, v156
	v_add_f32_e32 v152, v152, v153
	ds_bpermute_b32 v153, v159, v152
	v_mov_b32_e32 v156, v167
	v_mov_b32_e32 v166, v168
	v_mov_b32_e32 v167, v170
	v_lshlrev_b32_e32 v176, 16, v154
	s_waitcnt lgkmcnt(0)
	v_add_f32_e32 v152, v152, v153
	ds_bpermute_b32 v153, v160, v152
	v_and_b32_e32 v177, 0xffff0000, v154
	v_lshlrev_b32_e32 v154, 16, v148
	v_and_b32_e32 v179, 0xffff0000, v144
	v_and_b32_e32 v181, 0xffff0000, v142
	s_waitcnt lgkmcnt(0)
	v_add_f32_e32 v153, v152, v153
	ds_bpermute_b32 v175, v161, v153
	v_lshlrev_b32_e32 v152, 16, v155
	v_mov_b32_e32 v170, v169
	s_mov_b32 s15, 0x6800000
	s_waitcnt lgkmcnt(0)
	v_add_f32_e32 v175, v153, v175
	ds_bpermute_b32 v178, v162, v175
	v_and_b32_e32 v153, 0xffff0000, v155
	v_and_b32_e32 v155, 0xffff0000, v148
	v_lshlrev_b32_e32 v148, 16, v149
	v_and_b32_e32 v149, 0xffff0000, v149
	s_waitcnt lgkmcnt(0)
	v_add_f32_e32 v175, v175, v178
	ds_bpermute_b32 v180, v163, v175
	v_lshlrev_b32_e32 v178, 16, v144
	v_lshlrev_b32_e32 v144, 16, v145
	v_and_b32_e32 v145, 0xffff0000, v145
	s_waitcnt lgkmcnt(0)
	v_add_f32_e32 v175, v175, v180
	ds_bpermute_b32 v182, v164, v175
	v_lshlrev_b32_e32 v180, 16, v142
	v_lshlrev_b32_e32 v142, 16, v143
	v_and_b32_e32 v143, 0xffff0000, v143
	s_waitcnt lgkmcnt(0)
	v_add_f32_e32 v175, v175, v182
	v_fmamk_f32 v175, v175, 0x3a800000, v214
	v_rsq_f32_e32 v182, v175
	v_mov_b32_e32 v175, v165
	v_pk_mul_f32 v[166:167], v[182:183], v[166:167] op_sel_hi:[0,1]
	v_pk_mul_f32 v[184:185], v[182:183], v[184:185] op_sel_hi:[0,1]
	v_pk_mul_f32 v[156:157], v[182:183], v[156:157] op_sel_hi:[0,1]
	v_pk_fma_f32 v[154:155], v[6:7], v[166:167], v[154:155]
	v_pk_mul_f32 v[166:167], v[172:173], v[182:183] op_sel_hi:[1,0]
	v_pk_mul_f32 v[150:151], v[150:151], v[182:183] op_sel_hi:[1,0]
	v_pk_fma_f32 v[152:153], v[4:5], v[156:157], v[152:153]
	v_pk_fma_f32 v[156:157], v[2:3], v[184:185], v[176:177]
	v_pk_fma_f32 v[144:145], v[12:13], v[150:151], v[144:145]
	v_pk_fma_f32 v[150:151], v[10:11], v[166:167], v[178:179]
	v_pk_mul_f32 v[166:167], v[174:175], v[182:183] op_sel_hi:[1,0]
	v_pk_mul_f32 v[146:147], v[146:147], v[182:183] op_sel_hi:[1,0]
	v_pk_mul_f32 v[168:169], v[182:183], v[170:171] op_sel_hi:[0,1]
	v_pk_fma_f32 v[142:143], v[16:17], v[146:147], v[142:143]
	v_pk_fma_f32 v[146:147], v[14:15], v[166:167], v[180:181]
	v_mul_f32_e32 v165, v157, v157
	v_mul_f32_e32 v166, v153, v153
	v_pk_fma_f32 v[148:149], v[8:9], v[168:169], v[148:149]
	v_fmac_f32_e32 v165, v156, v156
	v_fmac_f32_e32 v166, v152, v152
	v_add_f32_e32 v165, v165, v166
	v_mul_f32_e32 v166, v155, v155
	v_mul_f32_e32 v167, v149, v149
	v_fmac_f32_e32 v166, v154, v154
	v_fmac_f32_e32 v167, v148, v148
	v_add_f32_e32 v166, v166, v167
	v_add_f32_e32 v165, v165, v166
	v_mul_f32_e32 v166, v151, v151
	v_mul_f32_e32 v167, v145, v145
	v_fmac_f32_e32 v166, v150, v150
	v_fmac_f32_e32 v167, v144, v144
	v_add_f32_e32 v166, v166, v167
	v_add_f32_e32 v165, v166, v165
	v_mul_f32_e32 v166, v147, v147
	v_mul_f32_e32 v167, v143, v143
	v_fmac_f32_e32 v166, v146, v146
	v_fmac_f32_e32 v167, v142, v142
	v_add_f32_e32 v166, v166, v167
	v_add_f32_e32 v165, v166, v165
	v_cvt_pk_bf16_f32 v168, v156, v157
	v_cvt_pk_bf16_f32 v169, v152, v153
	v_lshl_add_u64 v[166:167], s[28:29], 0, v[0:1]
	v_add_co_u32_e32 v166, vcc, s15, v166
	v_addc_co_u32_e32 v167, vcc, 0, v167, vcc
	global_store_dwordx2 v[166:167], v[168:169], off
	v_cvt_pk_bf16_f32 v168, v154, v155
	v_cvt_pk_bf16_f32 v169, v148, v149
	global_store_dwordx2 v[166:167], v[168:169], off offset:512
	v_cvt_pk_bf16_f32 v168, v150, v151
	v_cvt_pk_bf16_f32 v169, v144, v145
	s_waitcnt lgkmcnt(0)
	s_nop 1
	v_add_f32_dpp v165, v165, v165 quad_perm:[1,0,3,2] row_mask:0xf bank_mask:0xf
	s_nop 1
	v_add_f32_dpp v165, v165, v165 quad_perm:[2,3,0,1] row_mask:0xf bank_mask:0xf
	s_nop 1
	v_add_f32_dpp v165, v165, v165 row_half_mirror row_mask:0xf bank_mask:0xf
	s_nop 1
	v_add_f32_dpp v165, v165, v165 row_mirror row_mask:0xf bank_mask:0xf
	v_mov_b32_e32 v170, v165
	s_nop 1
	v_permlane16_swap_b32_e32 v165, v170
	v_add_f32_e32 v165, v165, v170
	v_mov_b32_e32 v170, v165
	s_nop 1
	v_permlane32_swap_b32_e32 v165, v170
	v_add_f32_e32 v165, v165, v170
	v_fmamk_f32 v165, v165, 0x3a800000, v214
	v_rsq_f32_e32 v165, v165
	global_store_dwordx2 v[166:167], v[168:169], off offset:1024
	v_cvt_pk_bf16_f32 v168, v146, v147
	v_cvt_pk_bf16_f32 v169, v142, v143
	global_store_dwordx2 v[166:167], v[168:169], off offset:1536
	s_and_saveexec_b64 s[30:31], s[4:5]
	s_cbranch_execz .LBB0_989
	global_store_dword v1, v165, s[22:23]

; __device__ __forceinline__ unsigned pk2(float lo, float hi) { const f32x2_pk v = {lo, hi}; return __builtin_bit_cast(unsigned, __builtin_convertvector(v, bf16x2_pk)); }
; __device__ __forceinline__ float bflo(unsigned w) { return __uint_as_float(w << 16); }
; __device__ __forceinline__ float bfhi(unsigned w) { return __uint_as_float(w & 0xffff0000u); }
; #define RS ((float*)(WSP() + WS_RS))
; template <bool HAS_G, bool HAS_PRE, bool HAS_F, bool HAS_P, bool HIN32, bool HOUT32> ...
;     ...
;         for (int j = 0; j < 4; ++j) { if (HIN32) v[j] = h32[u][j]; else v[j] = (f32x4){bflo(hbr[u][j].x), bfhi(hbr[u][j].x), bflo(hbr[u][j].y), bfhi(hbr[u][j].y)};
;             if (HAS_G) g[j] = (f32x4){bflo(gbr[u][j].x), bfhi(gbr[u][j].x), bflo(gbr[u][j].y), bfhi(gbr[u][j].y)}; }
;         if (m + 2 * NGW < M) E_LOAD(u, m + 2 * NGW);
;         if (HAS_G) {
;             float ss = 0.f;
; #pragma unroll
;             for (int j = 0; j < 4; ++j) ss += (g[j][0] * g[j][0] + g[j][1] * g[j][1]) + (g[j][2] * g[j][2] + g[j][3] * g[j][3]);
;             const float r = __builtin_amdgcn_rsqf(wave_sum(ss) * (1.f / DM) + EPS)    ;
; #pragma unroll
;             for (int j = 0; j < 4; ++j) { v[j] = v[j] + g[j] * r * gp[j];
;                 if (HOUT32) __builtin_nontemporal_store(v[j], (f32x4*)((float*)hout_ + mm * DM + 4 * lane + 256 * j));
;                 else { v2u w; w.x = pk2(v[j][0], v[j][1]); w.y = pk2(v[j][2], v[j][3]); *(v2u*)((bf16*)hout_ + mm * DM + 4 * lane + 256 * j) = w; } }
;         }
;         if (!HAS_G && hout_) {
; #pragma unroll
;             for (int j = 0; j < 4; ++j) { v2u w; w.x = pk2(v[j][0], v[j][1]); w.y = pk2(v[j][2], v[j][3]); *(v2u*)((bf16*)hout_ + mm * DM + 4 * lane + 256 * j) = w; } }
;         if (HAS_PRE) {
;             float ss = 0.f;
; #pragma unroll
;             for (int j = 0; j < 4; ++j) ss += (v[j][0] * v[j][0] + v[j][1] * v[j][1]) + (v[j][2] * v[j][2] + v[j][3] * v[j][3]);
;             const float r = __builtin_amdgcn_rsqf(wave_sum(ss) * (1.f / DM) + EPS)    ;
;             if (lane == 0) RS[mm] = r;
.LBB0_993:
	v_lshlrev_b32_e32 v167, 16, v141
	v_lshlrev_b32_e32 v166, 16, v140
	v_and_b32_e32 v141, 0xffff0000, v141
	v_and_b32_e32 v140, 0xffff0000, v140
	v_lshlrev_b32_e32 v174, 16, v134
	v_and_b32_e32 v165, 0xffff0000, v134
	v_lshlrev_b32_e32 v176, 16, v135
	v_and_b32_e32 v177, 0xffff0000, v135
	v_pk_mul_f32 v[134:135], v[140:141], v[140:141]
	v_lshlrev_b32_e32 v169, 16, v139
	v_lshlrev_b32_e32 v168, 16, v138
	v_and_b32_e32 v139, 0xffff0000, v139
	v_and_b32_e32 v138, 0xffff0000, v138
	v_pk_fma_f32 v[134:135], v[166:167], v[166:167], v[134:135]
	v_lshlrev_b32_e32 v170, 16, v136
	v_and_b32_e32 v171, 0xffff0000, v136
	v_lshlrev_b32_e32 v172, 16, v137
	v_and_b32_e32 v173, 0xffff0000, v137
	v_pk_add_f32 v[134:135], v[134:135], v[134:135] op_sel_hi:[0,1]
	v_pk_mul_f32 v[136:137], v[138:139], v[138:139]
	v_mul_f32_e32 v175, v170, v170
	v_pk_fma_f32 v[136:137], v[168:169], v[168:169], v[136:137]
	v_mul_f32_e32 v179, v171, v171
	v_mul_f32_e32 v134, v172, v172
	v_mov_b32_e32 v178, v174
	v_pk_add_f32 v[136:137], v[136:137], v[136:137] op_sel_hi:[0,1]
	v_pk_fma_f32 v[180:181], v[172:173], v[172:173], v[134:135] op_sel_hi:[1,1,0]
	v_pk_add_f32 v[178:179], v[174:175], v[178:179]
	v_mul_f32_e32 v180, v165, v165
	v_mul_f32_e32 v136, v176, v176
	v_mul_f32_e32 v134, v177, v177
	v_mul_f32_e32 v182, v174, v174
	v_mov_b32_e32 v183, v179
	v_pk_add_f32 v[178:179], v[182:183], v[180:181]
	v_pk_add_f32 v[134:135], v[136:137], v[134:135]
	v_lshlrev_b32_e32 v182, 16, v126
	v_pk_add_f32 v[134:135], v[178:179], v[134:135]
	v_and_b32_e32 v183, 0xffff0000, v126
	v_add_f32_e32 v134, v134, v135
	ds_bpermute_b32 v135, v159, v134
	v_lshlrev_b32_e32 v126, 16, v127
	v_and_b32_e32 v127, 0xffff0000, v127
	v_lshlrev_b32_e32 v178, 16, v130
	v_and_b32_e32 v179, 0xffff0000, v130
	s_waitcnt lgkmcnt(0)
	v_add_f32_e32 v134, v134, v135
	ds_bpermute_b32 v135, v160, v134
	v_lshlrev_b32_e32 v130, 16, v131
	v_and_b32_e32 v131, 0xffff0000, v131
	v_mov_b32_e32 v175, v165
	v_lshlrev_b32_e32 v180, 16, v128
	s_waitcnt lgkmcnt(0)
	v_add_f32_e32 v136, v134, v135
	ds_bpermute_b32 v137, v161, v136
	v_lshlrev_b32_e32 v134, 16, v132
	v_and_b32_e32 v135, 0xffff0000, v132
	v_lshlrev_b32_e32 v132, 16, v133
	v_and_b32_e32 v133, 0xffff0000, v133
	s_waitcnt lgkmcnt(0)
	v_add_f32_e32 v136, v136, v137
	ds_bpermute_b32 v137, v162, v136
	v_and_b32_e32 v181, 0xffff0000, v128
	v_lshlrev_b32_e32 v128, 16, v129
	v_and_b32_e32 v129, 0xffff0000, v129
	s_add_i32 s30, s70, s13
	s_waitcnt lgkmcnt(0)
	v_add_f32_e32 v136, v136, v137
	ds_bpermute_b32 v137, v163, v136
	s_ashr_i32 s31, s30, 31
	s_lshl_b64 s[34:35], s[30:31], 11
	s_waitcnt lgkmcnt(0)
	v_add_f32_e32 v136, v136, v137
	ds_bpermute_b32 v137, v164, v136
	s_waitcnt lgkmcnt(0)
	v_add_f32_e32 v136, v136, v137
	v_fmamk_f32 v136, v136, 0x3a800000, v214
	v_rsq_f32_e32 v184, v136
	v_mov_b32_e32 v136, v166
	v_mov_b32_e32 v137, v140
	v_mov_b32_e32 v140, v167
	v_pk_mul_f32 v[186:187], v[184:185], v[136:137] op_sel_hi:[0,1]
	v_pk_mul_f32 v[136:137], v[184:185], v[140:141] op_sel_hi:[0,1]
	v_pk_fma_f32 v[136:137], v[4:5], v[136:137], v[132:133]
	v_pk_fma_f32 v[140:141], v[2:3], v[186:187], v[134:135]
	v_mov_b32_e32 v132, v168
	v_mov_b32_e32 v133, v138
	v_mov_b32_e32 v138, v169
	v_pk_mul_f32 v[166:167], v[176:177], v[184:185] op_sel_hi:[1,0]
	v_pk_mul_f32 v[134:135], v[184:185], v[132:133] op_sel_hi:[0,1]
	v_pk_mul_f32 v[132:133], v[184:185], v[138:139] op_sel_hi:[0,1]
	v_pk_fma_f32 v[126:127], v[16:17], v[166:167], v[126:127]
	v_mul_f32_e32 v165, v141, v141
	v_mul_f32_e32 v166, v137, v137
	v_pk_fma_f32 v[132:133], v[8:9], v[132:133], v[130:131]
	v_pk_fma_f32 v[138:139], v[6:7], v[134:135], v[178:179]
	v_fmac_f32_e32 v165, v140, v140
	v_fmac_f32_e32 v166, v136, v136
	v_add_f32_e32 v165, v165, v166
	v_mul_f32_e32 v166, v139, v139
	v_mul_f32_e32 v167, v133, v133
	v_pk_mul_f32 v[130:131], v[170:171], v[184:185] op_sel_hi:[1,0]
	v_pk_mul_f32 v[134:135], v[172:173], v[184:185] op_sel_hi:[1,0]
	v_fmac_f32_e32 v166, v138, v138
	v_fmac_f32_e32 v167, v132, v132
	v_pk_fma_f32 v[128:129], v[12:13], v[134:135], v[128:129]
	v_pk_fma_f32 v[134:135], v[10:11], v[130:131], v[180:181]
	v_add_f32_e32 v166, v166, v167
	v_add_f32_e32 v165, v165, v166
	v_mul_f32_e32 v166, v135, v135
	v_mul_f32_e32 v167, v129, v129
	v_pk_mul_f32 v[130:131], v[174:175], v[184:185] op_sel_hi:[1,0]
	v_fmac_f32_e32 v166, v134, v134
	v_fmac_f32_e32 v167, v128, v128
	v_pk_fma_f32 v[130:131], v[14:15], v[130:131], v[182:183]
	v_add_f32_e32 v166, v166, v167
	v_add_f32_e32 v165, v166, v165
	v_mul_f32_e32 v166, v131, v131
	v_mul_f32_e32 v167, v127, v127
	v_fmac_f32_e32 v166, v130, v130
	v_fmac_f32_e32 v167, v126, v126
	v_add_f32_e32 v166, v166, v167
	v_add_f32_e32 v165, v166, v165
	v_cvt_pk_bf16_f32 v168, v140, v141
	v_lshl_add_u64 v[166:167], v[98:99], 0, s[34:35]
	v_cvt_pk_bf16_f32 v169, v136, v137
	global_store_dwordx2 v[166:167], v[168:169], off
	v_cvt_pk_bf16_f32 v168, v138, v139
	v_cvt_pk_bf16_f32 v169, v132, v133
	global_store_dwordx2 v[166:167], v[168:169], off offset:512
	v_cvt_pk_bf16_f32 v168, v134, v135
	v_cvt_pk_bf16_f32 v169, v128, v129
	global_store_dwordx2 v[166:167], v[168:169], off offset:1024
	s_waitcnt lgkmcnt(0)
	s_nop 1
	v_add_f32_dpp v165, v165, v165 quad_perm:[1,0,3,2] row_mask:0xf bank_mask:0xf
	s_nop 1
	v_add_f32_dpp v165, v165, v165 quad_perm:[2,3,0,1] row_mask:0xf bank_mask:0xf
	s_nop 1
	v_add_f32_dpp v165, v165, v165 row_half_mirror row_mask:0xf bank_mask:0xf
	s_nop 1
	v_add_f32_dpp v165, v165, v165 row_mirror row_mask:0xf bank_mask:0xf
	v_mov_b32_e32 v170, v165
	s_nop 1
	v_permlane16_swap_b32_e32 v165, v170
	v_add_f32_e32 v165, v165, v170
	v_mov_b32_e32 v170, v165
	s_nop 1
	v_permlane32_swap_b32_e32 v165, v170
	v_add_f32_e32 v165, v165, v170
	v_fmamk_f32 v165, v165, 0x3a800000, v214
	v_rsq_f32_e32 v165, v165
	v_cvt_pk_bf16_f32 v168, v130, v131
	v_cvt_pk_bf16_f32 v169, v126, v127
	global_store_dwordx2 v[166:167], v[168:169], off offset:1536
	s_and_saveexec_b64 s[34:35], s[4:5]
	s_cbranch_execz .LBB0_995
	s_lshl_b64 s[62:63], s[30:31], 2
	s_add_u32 s62, s48, s62
	s_addc_u32 s63, s49, s63
	global_store_dword v1, v165, s[62:63]
